# attention: waves 4-7 software-pipelined across the tile barrier (softmax+PV of tile t-1 overlaps partner QK of tile t)
# baseline (speedup 1.0000x reference)
; #define A_LOAD(t) do { kreg0 = *(const u32x4*)(kg + (size_t)((t) * 64 + kv0) * 768 + kc0 * 8); if (tid < 256) kreg1 = *(const u32x4*)(kg + (size_t)((t) * 64 + kv1) * 768 + kc1 * 8); \
;         vreg = *(const u32x4*)(vg + (size_t)(t) * 64 * 512); } while (0)
; __device__ __forceinline__ void attn_unit(LAS unsigned char* lds, const bf16* Q, const bf16* Kp, const bf16* V, bf16* Y, int b, int h, int qb) {
;     ...
;     const int kv0 = tid / 12, kc0 = tid % 12, kv1 = (tid + 512) / 12, kc1 = (tid + 512) % 12;
;     const bf16* kg = Kp + rowbase * 768 + h * 96;
;     const bf16* vg = V + (rowbase + (tid & 63)) * 512 + h * 64 + 8 * (tid >> 6);
;     u32x4 kreg0, kreg1 = (u32x4){0, 0, 0, 0}, vreg;
;     ...
;     A_LOAD(0); A_STORE(0);
;     __syncthreads();
;     float m_run = 0.f, l_run = 0.f;
;     f32x16 o[2];
; #pragma unroll
;     for (int i = 0; i < 16; ++i) { o[0][i] = 0.f; o[1][i] = 0.f; }
;     const int qrel = wid * 32 + r32;
;     for (int t = 0; t < NT; ++t) {
;         const int buf = t & 1;
;         if (t + 1 < NT) A_LOAD(t + 1);
.LBB0_3632:
	s_or_b64 exec, exec, s[10:11]
	v_and_b32_e32 v11, 63, v4
	v_or_b32_e32 v4, s13, v11
	v_lshlrev_b32_e32 v4, 10, v4
	v_mov_b32_e32 v5, v64
	v_lshl_add_u64 v[4:5], s[64:65], 0, v[4:5]
	s_lshl_b32 s80, s9, 7
	v_lshl_add_u64 v[14:15], v[4:5], 0, s[80:81]
	v_lshlrev_b32_e32 v4, 3, v8
	v_ashrrev_i32_e32 v5, 31, v4
	v_lshl_add_u64 v[14:15], v[4:5], 1, v[14:15]
	flat_load_dwordx4 v[100:103], v[14:15]
	s_movk_i32 s10, 0xd0
	v_mul_lo_u32 v65, v9, s10
	v_lshlrev_b32_e32 v111, 4, v12
	v_add3_u32 v12, 0, v65, v111
	v_lshlrev_b32_e32 v113, 4, v13
	s_waitcnt vmcnt(0) lgkmcnt(0)
	ds_write_b128 v12, v[92:95]
	s_and_saveexec_b64 s[10:11], vcc
	s_xor_b64 s[10:11], exec, s[10:11]
	v_lshlrev_b32_e32 v113, 4, v13
	s_or_saveexec_b64 s[10:11], s[10:11]
	s_movk_i32 s13, 0xd0
	v_mul_lo_u32 v114, v10, s13
	s_xor_b64 exec, exec, s[10:11]
	v_add3_u32 v12, 0, v114, v113
	ds_write_b128 v12, v[96:99]
	s_or_b64 exec, exec, s[10:11]
	v_lshl_add_u64 v[66:67], v[0:1], 1, s[6:7]
	v_lshl_add_u64 v[106:107], v[2:3], 1, s[6:7]
	s_movk_i32 s6, 0xd0
	v_lshlrev_b32_e32 v12, 3, v6
	v_mad_u32_u24 v0, v7, s6, 0
	v_mul_i32_i24_e32 v1, 0xffffffb8, v7
	v_lshl_add_u32 v117, v6, 4, v0
	v_add3_u32 v118, v0, v1, v12
	v_mov_b32_e32 v0, s80
	v_mov_b32_e32 v1, v64
	v_lshlrev_b32_e32 v2, 10, v11
	s_movk_i32 s10, 0x440
	v_lshl_add_u64 v[0:1], v[4:5], 1, v[0:1]
	v_lshl_or_b32 v2, s23, 23, v2
	v_mov_b32_e32 v3, v64
	s_lshl_b32 s12, s12, 2
	v_mul_lo_u32 v8, v8, s10
	v_lshlrev_b32_e32 v13, 1, v11
	v_lshlrev_b32_e32 v112, 2, v6
	s_lshl_b32 s15, s22, 8
	v_lshl_add_u64 v[0:1], v[0:1], 0, v[2:3]
	v_mov_b32_e32 v123, 0
	s_lshl_b32 s9, s9, 6
	s_add_i32 s12, s12, 4
	s_mov_b32 s13, 1
	v_add3_u32 v115, 0, v8, v13
	v_or_b32_e32 v116, s14, v7
	s_or_b32 s14, s14, 31
	v_or_b32_e32 v119, s15, v112
	s_lshl_b32 s22, s22, 2
	v_add_u32_e32 v120, 64, v10
	v_add_u32_e32 v121, 64, v9
	v_lshl_add_u64 v[108:109], s[4:5], 0, v[0:1]
	s_mov_b32 s23, 0
	v_mov_b32_e32 v122, 0
	v_mov_b32_e32 v16, 0
	v_mov_b32_e32 v17, v123
	v_mov_b32_e32 v18, v123
	v_mov_b32_e32 v19, v123
	v_mov_b32_e32 v20, v123
	v_mov_b32_e32 v21, v123
	v_mov_b32_e32 v22, v123
	v_mov_b32_e32 v23, v123
	v_mov_b32_e32 v24, v123
	v_mov_b32_e32 v25, v123
	v_mov_b32_e32 v26, v123
	v_mov_b32_e32 v27, v123
	v_mov_b32_e32 v28, v123
	v_mov_b32_e32 v29, v123
	v_mov_b32_e32 v30, v123
	v_mov_b32_e32 v31, v123
	v_mov_b32_e32 v0, v123
	v_mov_b32_e32 v1, v123
	v_mov_b32_e32 v2, v123
	v_mov_b32_e32 v3, v123
	v_mov_b32_e32 v4, v123
	v_mov_b32_e32 v5, v123
	v_mov_b32_e32 v6, v123
	v_mov_b32_e32 v7, v123
	v_mov_b32_e32 v8, v123
	v_mov_b32_e32 v9, v123
	v_mov_b32_e32 v10, v123
	v_mov_b32_e32 v11, v123
	v_mov_b32_e32 v12, v123
	v_mov_b32_e32 v13, v123
	v_mov_b32_e32 v14, v123
	v_mov_b32_e32 v15, v123
	ds_write_b16 v115, v100 offset:26624
	ds_write_b16_d16_hi v115, v100 offset:26760
	ds_write_b16 v115, v101 offset:26896
	ds_write_b16_d16_hi v115, v101 offset:27032
	ds_write_b16 v115, v102 offset:27168
	ds_write_b16_d16_hi v115, v102 offset:27304
	ds_write_b16 v115, v103 offset:27440
	ds_write_b16_d16_hi v115, v103 offset:27576
	v_mov_b32_e32 v142, 0
	v_mov_b32_e32 v143, 0
	v_mov_b32_e32 v144, 0
	v_mov_b32_e32 v145, 0
	v_mov_b32_e32 v146, 0
	v_mov_b32_e32 v147, 0
	v_mov_b32_e32 v148, 0
	v_mov_b32_e32 v149, 0
	v_mov_b32_e32 v150, 0
	v_mov_b32_e32 v151, 0
	v_mov_b32_e32 v152, 0
	v_mov_b32_e32 v153, 0
	v_mov_b32_e32 v154, 0
	v_mov_b32_e32 v155, 0
	v_mov_b32_e32 v156, 0
	v_mov_b32_e32 v157, 0
	s_mov_b64 s[66:67], -1
	s_waitcnt lgkmcnt(0)
	s_barrier
	s_mov_b32 s50, 0
	s_and_b64 vcc, exec, s[38:39]
	s_cbranch_vccz .LatB_head
	s_branch .Lat_head
.Lat_head:
	s_cmp_lt_u32 s13, s12
	s_cselect_b64 s[6:7], -1, 0
	s_cmp_ge_u32 s13, s12
	s_cbranch_scc1 .Lat_noloadA
	v_add_u32_e32 v32, s23, v121
	v_mad_i64_i32 v[32:33], s[10:11], v32, s87, v[66:67]
	s_waitcnt vmcnt(0)
	global_load_dwordx4 v[92:95], v[32:33], off
	v_add_u32_e32 v32, s23, v120
	v_mad_i64_i32 v[32:33], s[24:25], v32, s87, v[106:107]
	global_load_dwordx4 v[96:99], v[32:33], off
	global_load_dwordx4 v[100:103], v[108:109], off

; __device__ __forceinline__ void attn_unit(LAS unsigned char* lds, const bf16* Q, const bf16* Kp, const bf16* V, bf16* Y, int b, int h, int qb) {
;     ...
;         if (t + 1 < NT) A_STORE(buf ^ 1);
.Lat_stageA:
	s_andn2_b64 vcc, exec, s[6:7]
	s_cbranch_vccnz .Lat_latchA
	s_xor_b32 s10, s24, 1
	s_mul_i32 s6, s10, 0x3400
	s_add_i32 s11, s6, 0
	v_add3_u32 v110, s11, v65, v111
	s_waitcnt vmcnt(0) lgkmcnt(0)
	ds_write_b128 v110, v[92:95]
	v_add3_u32 v110, s11, v114, v113
	ds_write_b128 v110, v[96:99]
	s_mulk_i32 s10, 0x2200
	v_add_u32_e32 v110, s10, v115
	ds_write_b16 v110, v100 offset:26624
	ds_write_b16_d16_hi v110, v100 offset:26760
	ds_write_b16 v110, v101 offset:26896
	ds_write_b16_d16_hi v110, v101 offset:27032
	ds_write_b16 v110, v102 offset:27168
	ds_write_b16_d16_hi v110, v102 offset:27304
	ds_write_b16 v110, v103 offset:27440
	ds_write_b16_d16_hi v110, v103 offset:27576

; #define LAS __attribute__((address_space(3)))
; #define A_LOAD(t) do { kreg0 = *(const u32x4*)(kg + (size_t)((t) * 64 + kv0) * 768 + kc0 * 8); if (tid < 256) kreg1 = *(const u32x4*)(kg + (size_t)((t) * 64 + kv1) * 768 + kc1 * 8); \
;         vreg = *(const u32x4*)(vg + (size_t)(t) * 64 * 512); } while (0)
; __device__ __forceinline__ void attn_unit(LAS unsigned char* lds, const bf16* Q, const bf16* Kp, const bf16* V, bf16* Y, int b, int h, int qb) {
;     ...
;     for (int t = 0; t < NT; ++t) {
;         const int buf = t & 1;
;         if (t + 1 < NT) A_LOAD(t + 1);
;         const int jb = t - (NT - 4);
;         const bool skip = (jb >= 0) && (64 * jb > wid * 32 + 31);
;         if (!skip) {
;             f32x16 p0, p1;
;             const float nm = -m_run;
; #pragma unroll
;             for (int i = 0; i < 16; ++i) { p0[i] = nm; p1[i] = nm; }
;             LAS const unsigned char* kb = lds + KOFF + buf * KBUF + r32 * KPB + hi * 16;
;             LAS const unsigned char* vb = lds + VOFF + buf * VBUF + r32 * VPB + hi * 8;
; #pragma unroll
;             for (int d0 = 0; d0 < 6; ++d0) p0 = __builtin_amdgcn_mfma_f32_32x32x16_bf16(*(LAS const bf16x8*)(kb + 32 * d0), qr[d0], p0, 0, 0, 0);
; #pragma unroll
;             for (int d0 = 0; d0 < 6; ++d0) p1 = __builtin_amdgcn_mfma_f32_32x32x16_bf16(*(LAS const bf16x8*)(kb + 32 * KPB + 32 * d0), qr[d0], p1, 0, 0, 0);
.LatB_head:
	s_cmp_lt_u32 s13, s12
	s_cselect_b64 s[6:7], -1, 0
	s_cmp_ge_u32 s13, s12
	s_cbranch_scc1 .Lat_noloadB
	v_add_u32_e32 v126, s23, v121
	v_mad_i64_i32 v[126:127], s[10:11], v126, s87, v[66:67]
	s_waitcnt vmcnt(0)
	global_load_dwordx4 v[92:95], v[126:127], off
	global_load_dwordx4 v[100:103], v[108:109], off
.Lat_noloadB:
	s_cmp_eq_u32 s50, 0
	s_cbranch_scc1 .LatB_part2
	s_add_i32 s10, s22, s13
	s_addk_i32 s10, 0xff82
	s_cmp_gt_i32 s10, -1
	s_cselect_b64 s[10:11], -1, 0
	s_add_i32 s25, s15, s23
	s_addk_i32 s25, 0xe0c0
	s_cmp_gt_i32 s25, s14
	s_cselect_b64 s[26:27], -1, 0
	s_and_b64 s[26:27], s[10:11], s[26:27]
	s_and_b64 vcc, exec, s[26:27]
	s_cbranch_vccnz .LatB_part2
	s_andn2_b64 vcc, exec, s[10:11]
	s_cbranch_vccnz .Lat_nomask0B
	v_add_u32_e32 v126, s23, v119
	v_sub_u32_e32 v126, v116, v126
	v_add_u32_e32 v126, 0x1f40, v126
	v_cmp_gt_i32_e32 vcc, 0, v126
	v_cmp_gt_i32_e64 s[40:41], 1, v126
	v_cmp_gt_i32_e64 s[42:43], 2, v126
	v_cndmask_b32_e32 v32, v32, v221, vcc
	v_cmp_gt_i32_e32 vcc, 3, v126
	v_cndmask_b32_e64 v33, v33, v221, s[40:41]
	v_cmp_gt_i32_e64 s[40:41], 8, v126
	v_cndmask_b32_e64 v34, v34, v221, s[42:43]
	v_cmp_gt_i32_e64 s[42:43], 9, v126
	v_cndmask_b32_e32 v35, v35, v221, vcc
	v_cmp_gt_i32_e32 vcc, 10, v126
	v_cndmask_b32_e64 v36, v36, v221, s[40:41]
	v_cmp_gt_i32_e64 s[40:41], 11, v126
	v_cndmask_b32_e64 v37, v37, v221, s[42:43]
	v_cmp_gt_i32_e64 s[42:43], 16, v126
	v_cndmask_b32_e32 v38, v38, v221, vcc
	v_cmp_gt_i32_e32 vcc, 17, v126
	v_cndmask_b32_e64 v39, v39, v221, s[40:41]
	v_cmp_gt_i32_e64 s[40:41], 18, v126
	v_cndmask_b32_e64 v40, v40, v221, s[42:43]
	v_cmp_gt_i32_e64 s[42:43], 19, v126
	v_cndmask_b32_e32 v41, v41, v221, vcc
	v_cmp_gt_i32_e32 vcc, 24, v126
	v_cndmask_b32_e64 v42, v42, v221, s[40:41]
	v_cmp_gt_i32_e64 s[40:41], 25, v126
	v_cndmask_b32_e64 v43, v43, v221, s[42:43]
	v_cmp_gt_i32_e64 s[42:43], 26, v126
	v_cndmask_b32_e32 v44, v44, v221, vcc
	v_cmp_gt_i32_e32 vcc, 27, v126
	v_cndmask_b32_e64 v45, v45, v221, s[40:41]
	v_cndmask_b32_e64 v46, v46, v221, s[42:43]
	s_nop 0
	v_cndmask_b32_e32 v47, v47, v221, vcc
.Lat_nomask0B:
	v_exp_f32_e32 v172, v32
	v_exp_f32_e32 v173, v33
	v_exp_f32_e32 v174, v34
	v_exp_f32_e32 v175, v35
	v_exp_f32_e32 v176, v36
	v_exp_f32_e32 v177, v37
	v_exp_f32_e32 v178, v38
	v_exp_f32_e32 v179, v39
	v_exp_f32_e32 v180, v40
	v_exp_f32_e32 v181, v41
	v_exp_f32_e32 v182, v42
	v_exp_f32_e32 v183, v43
	v_exp_f32_e32 v184, v44
	v_exp_f32_e32 v185, v45
	v_exp_f32_e32 v186, v46
	v_exp_f32_e32 v187, v47
	v_add_f32_e32 v138, v172, v174
	v_add_f32_e32 v139, v173, v175
	v_cvt_pk_bf16_f32 v130, v172, v173
	v_cvt_pk_bf16_f32 v131, v174, v175
	v_add_f32_e32 v138, v138, v176
	v_add_f32_e32 v139, v139, v177
	v_cvt_pk_bf16_f32 v132, v176, v177
	v_add_f32_e32 v138, v138, v178
	v_add_f32_e32 v139, v139, v179
	v_cvt_pk_bf16_f32 v133, v178, v179
	v_add_f32_e32 v138, v138, v180
	v_add_f32_e32 v139, v139, v181
	v_cvt_pk_bf16_f32 v134, v180, v181
	v_add_f32_e32 v138, v138, v182
	v_add_f32_e32 v139, v139, v183
	v_cvt_pk_bf16_f32 v135, v182, v183
	v_add_f32_e32 v138, v138, v184
	v_add_f32_e32 v139, v139, v185
	v_cvt_pk_bf16_f32 v136, v184, v185
	v_add_f32_e32 v138, v138, v186
	v_add_f32_e32 v139, v139, v187
	v_cvt_pk_bf16_f32 v137, v186, v187
	v_add_f32_e32 v138, v138, v139
	v_cmp_lt_f32_e32 vcc, 0x43800000, v138
	s_or_b64 vcc, vcc, s[66:67]
	s_cbranch_vccnz .Lat_slow0B
.Lat_cont0B:
	v_add_f32_e32 v123, v123, v138
	v_mfma_f32_32x32x16_bf16 v[16:31], v[234:237], v[130:133], v[16:31]
	s_andn2_b64 vcc, exec, s[10:11]
	s_cbranch_vccnz .Lat_nomask1B
	v_add_u32_e32 v126, s23, v119
	v_sub_u32_e32 v126, v116, v126
	v_add_u32_e32 v126, 0x1f40, v126
	v_cmp_gt_i32_e32 vcc, 32, v126
	v_cmp_gt_i32_e64 s[40:41], 33, v126
	v_cmp_gt_i32_e64 s[42:43], 34, v126
	v_cndmask_b32_e32 v48, v48, v221, vcc
	v_cmp_gt_i32_e32 vcc, 35, v126
	v_cndmask_b32_e64 v49, v49, v221, s[40:41]
	v_cmp_gt_i32_e64 s[40:41], 40, v126
	v_cndmask_b32_e64 v50, v50, v221, s[42:43]
	v_cmp_gt_i32_e64 s[42:43], 41, v126
	v_cndmask_b32_e32 v51, v51, v221, vcc
	v_cmp_gt_i32_e32 vcc, 42, v126
	v_cndmask_b32_e64 v52, v52, v221, s[40:41]
	v_cmp_gt_i32_e64 s[40:41], 43, v126
	v_cndmask_b32_e64 v53, v53, v221, s[42:43]
	v_cmp_gt_i32_e64 s[42:43], 48, v126
	v_cndmask_b32_e32 v54, v54, v221, vcc
	v_cmp_gt_i32_e32 vcc, 49, v126
	v_cndmask_b32_e64 v55, v55, v221, s[40:41]
	v_cmp_gt_i32_e64 s[40:41], 50, v126
	v_cndmask_b32_e64 v56, v56, v221, s[42:43]
	v_cmp_gt_i32_e64 s[42:43], 51, v126
	v_cndmask_b32_e32 v57, v57, v221, vcc
	v_cmp_gt_i32_e32 vcc, 56, v126
	v_cndmask_b32_e64 v58, v58, v221, s[40:41]
	v_cmp_gt_i32_e64 s[40:41], 57, v126
	v_cndmask_b32_e64 v59, v59, v221, s[42:43]
	v_cmp_gt_i32_e64 s[42:43], 58, v126
	v_cndmask_b32_e32 v60, v60, v221, vcc
	v_cmp_gt_i32_e32 vcc, 59, v126
	v_cndmask_b32_e64 v61, v61, v221, s[40:41]
	v_cndmask_b32_e64 v62, v62, v221, s[42:43]
	s_nop 0
	v_cndmask_b32_e32 v63, v63, v221, vcc

; #define LAS __attribute__((address_space(3)))
; #define A_LOAD(t) do { kreg0 = *(const u32x4*)(kg + (size_t)((t) * 64 + kv0) * 768 + kc0 * 8); if (tid < 256) kreg1 = *(const u32x4*)(kg + (size_t)((t) * 64 + kv1) * 768 + kc1 * 8); \
;         vreg = *(const u32x4*)(vg + (size_t)(t) * 64 * 512); } while (0)
; __device__ __forceinline__ void attn_unit(LAS unsigned char* lds, const bf16* Q, const bf16* Kp, const bf16* V, bf16* Y, int b, int h, int qb) {
;     ...
;         if (t + 1 < NT) A_LOAD(t + 1);
;         const int jb = t - (NT - 4);
;         const bool skip = (jb >= 0) && (64 * jb > wid * 32 + 31);
;         if (!skip) {
;             f32x16 p0, p1;
;             const float nm = -m_run;
; #pragma unroll
;             for (int i = 0; i < 16; ++i) { p0[i] = nm; p1[i] = nm; }
;             LAS const unsigned char* kb = lds + KOFF + buf * KBUF + r32 * KPB + hi * 16;
;             LAS const unsigned char* vb = lds + VOFF + buf * VBUF + r32 * VPB + hi * 8;
; #pragma unroll
;             for (int d0 = 0; d0 < 6; ++d0) p0 = __builtin_amdgcn_mfma_f32_32x32x16_bf16(*(LAS const bf16x8*)(kb + 32 * d0), qr[d0], p0, 0, 0, 0);
; #pragma unroll
;             for (int d0 = 0; d0 < 6; ++d0) p1 = __builtin_amdgcn_mfma_f32_32x32x16_bf16(*(LAS const bf16x8*)(kb + 32 * KPB + 32 * d0), qr[d0], p1, 0, 0, 0);
;     ...
;             ATT_HALF(p0, 0, 0);
;             ATT_HALF(p1, 32, 2);
;     ...
;         }
;         if (t + 1 < NT) A_STORE(buf ^ 1);
.Lat_cont1B:
	v_add_f32_e32 v123, v123, v138
	v_mfma_f32_32x32x16_bf16 v[16:31], v[198:201], v[130:133], v[16:31]
	v_mfma_f32_32x32x16_bf16 v[0:15], v[206:209], v[130:133], v[0:15]
	v_mfma_f32_32x32x16_bf16 v[16:31], v[202:205], v[134:137], v[16:31]
	v_mfma_f32_32x32x16_bf16 v[0:15], v[222:225], v[134:137], v[0:15]
.LatB_part2:
	s_cmp_gt_u32 s13, s12
	s_cbranch_scc1 .LBB0_3656
	s_add_i32 s10, s13, -1
	s_and_b32 s24, s10, 1
	s_add_i32 s10, s22, s13
	s_addk_i32 s10, 0xff83
	s_cmp_gt_i32 s10, -1
	s_cselect_b64 s[10:11], -1, 0
	s_add_i32 s25, s15, s23
	s_addk_i32 s25, 0xe100
	s_cmp_gt_i32 s25, s14
	s_cselect_b64 s[26:27], -1, 0
	s_and_b64 s[26:27], s[10:11], s[26:27]
	s_and_b64 vcc, exec, s[26:27]
	s_cbranch_vccnz .Lat_stageB
	s_mul_i32 s25, s24, 0x3400
	v_add_u32_e32 v110, s25, v117
	s_mul_i32 s25, s24, 0x2200
	v_add_u32_e32 v125, s25, v118
	ds_read_b128 v[172:175], v110
	ds_read_b128 v[176:179], v110 offset:32
	ds_read_b128 v[180:183], v110 offset:64
	ds_read_b128 v[184:187], v110 offset:96
	ds_read_b128 v[188:191], v110 offset:128
	ds_read_b128 v[192:195], v110 offset:160
	ds_read_b128 v[198:201], v110 offset:6656
	ds_read_b128 v[202:205], v110 offset:6688
	ds_read_b128 v[206:209], v110 offset:6720
	ds_read_b128 v[222:225], v110 offset:6752
	ds_read_b128 v[226:229], v110 offset:6784
	ds_read_b128 v[230:233], v110 offset:6816
	v_add_u32_e32 v124, 0x6800, v125
	v_add_u32_e32 v125, 0x7800, v125
	s_waitcnt lgkmcnt(11)
	v_mfma_f32_32x32x16_bf16 v[32:47], v[172:175], v[68:71], v[142:157]
	ds_read2_b64 v[234:237], v124 offset1:2
	s_waitcnt lgkmcnt(11)
	v_mfma_f32_32x32x16_bf16 v[32:47], v[176:179], v[72:75], v[32:47]
	ds_read2_b64 v[238:241], v124 offset0:4 offset1:6
	s_waitcnt lgkmcnt(11)
	v_mfma_f32_32x32x16_bf16 v[32:47], v[180:183], v[76:79], v[32:47]
	ds_read2_b64 v[242:245], v125 offset0:32 offset1:34
	s_waitcnt lgkmcnt(11)
	v_mfma_f32_32x32x16_bf16 v[32:47], v[184:187], v[80:83], v[32:47]
	ds_read2_b64 v[246:249], v125 offset0:36 offset1:38
	s_waitcnt lgkmcnt(11)
	v_mfma_f32_32x32x16_bf16 v[32:47], v[188:191], v[84:87], v[32:47]
	s_waitcnt lgkmcnt(10)
	v_mfma_f32_32x32x16_bf16 v[32:47], v[192:195], v[88:91], v[32:47]
	s_waitcnt lgkmcnt(9)
	v_mfma_f32_32x32x16_bf16 v[48:63], v[198:201], v[68:71], v[142:157]
	s_waitcnt lgkmcnt(8)
	v_mfma_f32_32x32x16_bf16 v[48:63], v[202:205], v[72:75], v[48:63]
	s_waitcnt lgkmcnt(7)
	v_mfma_f32_32x32x16_bf16 v[48:63], v[206:209], v[76:79], v[48:63]
	s_waitcnt lgkmcnt(6)
	v_mfma_f32_32x32x16_bf16 v[48:63], v[222:225], v[80:83], v[48:63]
	s_waitcnt lgkmcnt(5)
	v_mfma_f32_32x32x16_bf16 v[48:63], v[226:229], v[84:87], v[48:63]
	s_waitcnt lgkmcnt(4)
	v_mfma_f32_32x32x16_bf16 v[48:63], v[230:233], v[88:91], v[48:63]
	ds_read2_b64 v[198:201], v124 offset0:8 offset1:10
	ds_read2_b64 v[202:205], v124 offset0:12 offset1:14
	ds_read2_b64 v[206:209], v125 offset0:40 offset1:42
	ds_read2_b64 v[222:225], v125 offset0:44 offset1:46
.Lat_stageB:
	s_andn2_b64 vcc, exec, s[6:7]
	s_cbranch_vccnz .Lat_latchB
	s_xor_b32 s10, s24, 1
	s_mul_i32 s6, s10, 0x3400
	s_add_i32 s11, s6, 0
	v_add3_u32 v110, s11, v65, v111
	s_waitcnt vmcnt(0) lgkmcnt(0)
	ds_write_b128 v110, v[92:95]
	s_mulk_i32 s10, 0x2200
	v_add_u32_e32 v110, s10, v115
	ds_write_b16 v110, v100 offset:26624
	ds_write_b16_d16_hi v110, v100 offset:26760
	ds_write_b16 v110, v101 offset:26896
	ds_write_b16_d16_hi v110, v101 offset:27032
	ds_write_b16 v110, v102 offset:27168
	ds_write_b16_d16_hi v110, v102 offset:27304
	ds_write_b16 v110, v103 offset:27440
	ds_write_b16_d16_hi v110, v103 offset:27576
.Lat_latchB:
	s_mov_b32 s50, 1
	s_add_i32 s13, s13, 1
	s_add_i32 s23, s23, 64
	s_mov_b64 s[6:7], 0x10000
	v_lshl_add_u64 v[108:109], v[108:109], 0, s[6:7]
	s_waitcnt lgkmcnt(0)
	s_barrier
	s_branch .LatB_head

.Lat_slow1A:
	s_nop 7
	v_max3_f32 v127, v48, v49, v50
	v_max3_f32 v128, v51, v52, v53
	v_max3_f32 v127, v127, v54, v55
	v_max3_f32 v128, v128, v56, v57
	v_max3_f32 v127, v127, v58, v59
	v_max3_f32 v128, v128, v60, v61
	v_max3_f32 v127, v127, v62, v63
	v_max_f32_e32 v127, v127, v128
	v_mov_b32_e32 v128, v127
	s_nop 1
	v_permlane32_swap_b32_e32 v127, v128
	v_max_f32_e32 v127, v127, v128
	v_max_f32_e32 v128, 0, v127
	v_exp_f32_e64 v129, -v128
	v_add_f32_e32 v122, v122, v128
	v_sub_f32_e32 v48, v48, v128
	v_sub_f32_e32 v49, v49, v128
	v_sub_f32_e32 v50, v50, v128
	v_sub_f32_e32 v51, v51, v128
	v_sub_f32_e32 v52, v52, v128
	v_sub_f32_e32 v53, v53, v128
	v_sub_f32_e32 v54, v54, v128
	v_sub_f32_e32 v55, v55, v128
	v_sub_f32_e32 v56, v56, v128
	v_sub_f32_e32 v57, v57, v128
	v_sub_f32_e32 v58, v58, v128
	v_sub_f32_e32 v59, v59, v128
	v_sub_f32_e32 v60, v60, v128
	v_sub_f32_e32 v61, v61, v128
	v_sub_f32_e32 v62, v62, v128
	v_sub_f32_e32 v63, v63, v128
	v_sub_f32_e32 v142, v142, v128
	v_sub_f32_e32 v143, v143, v128
	v_sub_f32_e32 v144, v144, v128
	v_sub_f32_e32 v145, v145, v128
	v_sub_f32_e32 v146, v146, v128
	v_sub_f32_e32 v147, v147, v128
	v_sub_f32_e32 v148, v148, v128
	v_sub_f32_e32 v149, v149, v128
	v_sub_f32_e32 v150, v150, v128
	v_sub_f32_e32 v151, v151, v128
	v_sub_f32_e32 v152, v152, v128
	v_sub_f32_e32 v153, v153, v128
	v_sub_f32_e32 v154, v154, v128
	v_sub_f32_e32 v155, v155, v128
	v_sub_f32_e32 v156, v156, v128
	v_sub_f32_e32 v157, v157, v128
	v_mul_f32_e32 v0, v0, v129
	v_mul_f32_e32 v1, v1, v129
	v_mul_f32_e32 v2, v2, v129
	v_mul_f32_e32 v3, v3, v129
	v_mul_f32_e32 v4, v4, v129
	v_mul_f32_e32 v5, v5, v129
	v_mul_f32_e32 v6, v6, v129
	v_mul_f32_e32 v7, v7, v129
	v_mul_f32_e32 v8, v8, v129
	v_mul_f32_e32 v9, v9, v129
	v_mul_f32_e32 v10, v10, v129
	v_mul_f32_e32 v11, v11, v129
	v_mul_f32_e32 v12, v12, v129
	v_mul_f32_e32 v13, v13, v129
	v_mul_f32_e32 v14, v14, v129
	v_mul_f32_e32 v15, v15, v129
	v_mul_f32_e32 v16, v16, v129
	v_mul_f32_e32 v17, v17, v129
	v_mul_f32_e32 v18, v18, v129
	v_mul_f32_e32 v19, v19, v129
	v_mul_f32_e32 v20, v20, v129
	v_mul_f32_e32 v21, v21, v129
	v_mul_f32_e32 v22, v22, v129
	v_mul_f32_e32 v23, v23, v129
	v_mul_f32_e32 v24, v24, v129
	v_mul_f32_e32 v25, v25, v129
	v_mul_f32_e32 v26, v26, v129
	v_mul_f32_e32 v27, v27, v129
	v_mul_f32_e32 v28, v28, v129
	v_mul_f32_e32 v29, v29, v129
	v_mul_f32_e32 v30, v30, v129
	v_mul_f32_e32 v31, v31, v129
	v_mul_f32_e32 v123, v123, v129
	v_exp_f32_e32 v188, v48
	v_exp_f32_e32 v189, v49
	v_exp_f32_e32 v190, v50
	v_exp_f32_e32 v191, v51
	v_exp_f32_e32 v192, v52
	v_exp_f32_e32 v193, v53
	v_exp_f32_e32 v194, v54
	v_exp_f32_e32 v195, v55
	v_exp_f32_e32 v216, v56
	v_exp_f32_e32 v217, v57
	v_exp_f32_e32 v218, v58
	v_exp_f32_e32 v219, v59
	v_exp_f32_e32 v250, v60
	v_exp_f32_e32 v251, v61
	v_exp_f32_e32 v140, v62
	v_exp_f32_e32 v141, v63
	v_add_f32_e32 v138, v188, v190
	v_add_f32_e32 v139, v189, v191
	v_cvt_pk_bf16_f32 v130, v188, v189
	v_cvt_pk_bf16_f32 v131, v190, v191
	v_add_f32_e32 v138, v138, v192
	v_add_f32_e32 v139, v139, v193
	v_cvt_pk_bf16_f32 v132, v192, v193
	v_add_f32_e32 v138, v138, v194
	v_add_f32_e32 v139, v139, v195
	v_cvt_pk_bf16_f32 v133, v194, v195
	v_add_f32_e32 v138, v138, v216
	v_add_f32_e32 v139, v139, v217
	v_cvt_pk_bf16_f32 v134, v216, v217
	v_add_f32_e32 v138, v138, v218
	v_add_f32_e32 v139, v139, v219
	v_cvt_pk_bf16_f32 v135, v218, v219
	v_add_f32_e32 v138, v138, v250
	v_add_f32_e32 v139, v139, v251
	v_cvt_pk_bf16_f32 v136, v250, v251
	v_add_f32_e32 v138, v138, v140
	v_add_f32_e32 v139, v139, v141
	v_cvt_pk_bf16_f32 v137, v140, v141
	v_add_f32_e32 v138, v138, v139
	s_branch .Lat_cont1A
.Lat_slow0B:
	s_nop 7
	v_max3_f32 v127, v32, v33, v34
	v_max3_f32 v128, v35, v36, v37
	v_max3_f32 v127, v127, v38, v39
	v_max3_f32 v128, v128, v40, v41
	v_max3_f32 v127, v127, v42, v43
	v_max3_f32 v128, v128, v44, v45
	v_max3_f32 v127, v127, v46, v47
	v_max_f32_e32 v127, v127, v128
	v_mov_b32_e32 v128, v127
	s_nop 1
	v_permlane32_swap_b32_e32 v127, v128
	v_max_f32_e32 v127, v127, v128
	v_max_f32_e32 v128, 0, v127
	s_nop 0
	v_cndmask_b32_e64 v128, v128, v127, s[66:67]
	s_mov_b64 s[66:67], 0
	v_exp_f32_e64 v129, -v128
	v_add_f32_e32 v122, v122, v128
	v_sub_f32_e32 v32, v32, v128
	v_sub_f32_e32 v33, v33, v128
	v_sub_f32_e32 v34, v34, v128
	v_sub_f32_e32 v35, v35, v128
	v_sub_f32_e32 v36, v36, v128
	v_sub_f32_e32 v37, v37, v128
	v_sub_f32_e32 v38, v38, v128
	v_sub_f32_e32 v39, v39, v128
	v_sub_f32_e32 v40, v40, v128
	v_sub_f32_e32 v41, v41, v128
	v_sub_f32_e32 v42, v42, v128
	v_sub_f32_e32 v43, v43, v128
	v_sub_f32_e32 v44, v44, v128
	v_sub_f32_e32 v45, v45, v128
	v_sub_f32_e32 v46, v46, v128
	v_sub_f32_e32 v47, v47, v128
	v_sub_f32_e32 v48, v48, v128
	v_sub_f32_e32 v49, v49, v128
	v_sub_f32_e32 v50, v50, v128
	v_sub_f32_e32 v51, v51, v128
	v_sub_f32_e32 v52, v52, v128
	v_sub_f32_e32 v53, v53, v128
	v_sub_f32_e32 v54, v54, v128
	v_sub_f32_e32 v55, v55, v128
	v_sub_f32_e32 v56, v56, v128
	v_sub_f32_e32 v57, v57, v128
	v_sub_f32_e32 v58, v58, v128
	v_sub_f32_e32 v59, v59, v128
	v_sub_f32_e32 v60, v60, v128
	v_sub_f32_e32 v61, v61, v128
	v_sub_f32_e32 v62, v62, v128
	v_sub_f32_e32 v63, v63, v128
	v_sub_f32_e32 v142, v142, v128
	v_sub_f32_e32 v143, v143, v128
	v_sub_f32_e32 v144, v144, v128
	v_sub_f32_e32 v145, v145, v128
	v_sub_f32_e32 v146, v146, v128
	v_sub_f32_e32 v147, v147, v128
	v_sub_f32_e32 v148, v148, v128
	v_sub_f32_e32 v149, v149, v128
	v_sub_f32_e32 v150, v150, v128
	v_sub_f32_e32 v151, v151, v128
	v_sub_f32_e32 v152, v152, v128
	v_sub_f32_e32 v153, v153, v128
	v_sub_f32_e32 v154, v154, v128
	v_sub_f32_e32 v155, v155, v128
	v_sub_f32_e32 v156, v156, v128
	v_sub_f32_e32 v157, v157, v128
	v_mul_f32_e32 v0, v0, v129
	v_mul_f32_e32 v1, v1, v129
	v_mul_f32_e32 v2, v2, v129
	v_mul_f32_e32 v3, v3, v129
	v_mul_f32_e32 v4, v4, v129
	v_mul_f32_e32 v5, v5, v129
	v_mul_f32_e32 v6, v6, v129
	v_mul_f32_e32 v7, v7, v129
	v_mul_f32_e32 v8, v8, v129
	v_mul_f32_e32 v9, v9, v129
	v_mul_f32_e32 v10, v10, v129
	v_mul_f32_e32 v11, v11, v129
	v_mul_f32_e32 v12, v12, v129
	v_mul_f32_e32 v13, v13, v129
	v_mul_f32_e32 v14, v14, v129
	v_mul_f32_e32 v15, v15, v129
	v_mul_f32_e32 v16, v16, v129
	v_mul_f32_e32 v17, v17, v129
	v_mul_f32_e32 v18, v18, v129
	v_mul_f32_e32 v19, v19, v129
	v_mul_f32_e32 v20, v20, v129
	v_mul_f32_e32 v21, v21, v129
	v_mul_f32_e32 v22, v22, v129
	v_mul_f32_e32 v23, v23, v129
	v_mul_f32_e32 v24, v24, v129
	v_mul_f32_e32 v25, v25, v129
	v_mul_f32_e32 v26, v26, v129
	v_mul_f32_e32 v27, v27, v129
	v_mul_f32_e32 v28, v28, v129
	v_mul_f32_e32 v29, v29, v129
	v_mul_f32_e32 v30, v30, v129
	v_mul_f32_e32 v31, v31, v129
	v_mul_f32_e32 v123, v123, v129
	v_exp_f32_e32 v172, v32
	v_exp_f32_e32 v173, v33
	v_exp_f32_e32 v174, v34
	v_exp_f32_e32 v175, v35
	v_exp_f32_e32 v176, v36
	v_exp_f32_e32 v177, v37
	v_exp_f32_e32 v178, v38
	v_exp_f32_e32 v179, v39
	v_exp_f32_e32 v180, v40
	v_exp_f32_e32 v181, v41
	v_exp_f32_e32 v182, v42
	v_exp_f32_e32 v183, v43
	v_exp_f32_e32 v184, v44
	v_exp_f32_e32 v185, v45
	v_exp_f32_e32 v186, v46
	v_exp_f32_e32 v187, v47
	v_add_f32_e32 v138, v172, v174
	v_add_f32_e32 v139, v173, v175
	v_cvt_pk_bf16_f32 v130, v172, v173
	v_cvt_pk_bf16_f32 v131, v174, v175
	v_add_f32_e32 v138, v138, v176
	v_add_f32_e32 v139, v139, v177
	v_cvt_pk_bf16_f32 v132, v176, v177
	v_add_f32_e32 v138, v138, v178
	v_add_f32_e32 v139, v139, v179
	v_cvt_pk_bf16_f32 v133, v178, v179
	v_add_f32_e32 v138, v138, v180
	v_add_f32_e32 v139, v139, v181
	v_cvt_pk_bf16_f32 v134, v180, v181
	v_add_f32_e32 v138, v138, v182
	v_add_f32_e32 v139, v139, v183
	v_cvt_pk_bf16_f32 v135, v182, v183
	v_add_f32_e32 v138, v138, v184
	v_add_f32_e32 v139, v139, v185
	v_cvt_pk_bf16_f32 v136, v184, v185
	v_add_f32_e32 v138, v138, v186
	v_add_f32_e32 v139, v139, v187
	v_cvt_pk_bf16_f32 v137, v186, v187
	v_add_f32_e32 v138, v138, v139
	s_branch .Lat_cont0B
